# XCD-local barrier: acquire with workgroup-level cache invalidate instead of device-level (all consumers share the XCD L2)
# speedup vs baseline: 1.0050x; 1.0042x over previous
.Llb_do:
	s_waitcnt vmcnt(0) lgkmcnt(0)
	s_barrier
	v_readlane_b32 s8, v255, 52
	s_add_i32 s8, s8, 1
	v_writelane_b32 v255, s8, 52
	s_mov_b64 s[10:11], exec
	v_readlane_b32 s2, v254, 0
	v_readlane_b32 s3, v254, 1
	s_and_b64 s[2:3], s[10:11], s[2:3]
	s_mov_b64 exec, s[2:3]
	s_cbranch_execz .Llb_done
	s_and_b32 s9, s82, 7
	s_lshl_b32 s9, s9, 8
	s_addk_i32 s9, 0x480
	v_mov_b32_e32 v0, s9
	v_mov_b32_e32 v1, 1
	global_atomic_add v2, v0, v1, s[4:5] sc0
	buffer_inv sc0
	v_add_u32_e32 v0, 0x2000, v0
	s_waitcnt vmcnt(0)
	v_readfirstlane_b32 s9, v2
	s_add_i32 s9, s9, 1
	s_lshl_b32 s13, s8, 6
	s_cmp_eq_u32 s9, s13
	s_cbranch_scc0 .Llb_wait
	global_atomic_add v0, v1, s[4:5]
	s_branch .Llb_done
